# P10: s_barrier at the top of every gather round (waves of a workgroup re-aligned on the expert-range walk)
# speedup vs baseline: 1.0169x; 1.0169x over previous
; __device__ __forceinline__ void phase10(const Args& a, LAS unsigned char* lds, int tid, int wave, int lane, int vcu, int G, int emask, bool probe) {
;     ...
;     for (int rd = 0; rd < nrounds; ++rd) {
;         u32x4 hq[GTK]; float sh[GTK];
; #pragma unroll
;         for (int tk = 0; tk < GTK; ++tk) {
;             const int slot = GTK * rd + tk;
;             const size_t R = G == 256 ? ((slot < 8 || (slot == 8 && wave < 4)) ? (size_t)68 * vcu + (slot < 8 ? wave + 8 * slot : 64 + wave) : (size_t)MT) : (size_t)gw + (size_t)slot * NGW;
.LBB0_1663:
	s_barrier
	s_mul_i32 s60, s38, 3
	s_and_b64 vcc, exec, s[12:13]
	s_mul_i32 s53, s60, s42
	s_mul_hi_u32 s54, s60, s37
	s_mul_i32 s55, s60, s37
	s_mov_b64 s[8:9], -1
	s_cbranch_vccz .LBB0_1665
	s_add_i32 s8, s54, s53
	s_add_u32 s10, s55, s36
	s_addc_u32 s11, s8, s41
	s_mov_b64 s[8:9], 0
